# added: StaticOrder division estimate constant-folded (group size is always 8), removing a rcp/readfirstlane chain per unit
# baseline (speedup 1.0000x reference)
.LBB0_203:
	s_add_i32 s87, s87, 1
	s_mul_i32 s4, s87, s33
	s_mul_hi_u32 s5, s87, s38
	s_add_i32 s5, s5, s4
	s_mul_i32 s4, s87, s38
	s_add_u32 s64, s4, s2
	s_addc_u32 s65, s5, s3
	v_cmp_gt_i64_e32 vcc, s[64:65], v[158:159]
	v_cmp_lt_i64_e64 s[4:5], s[64:65], v[156:157]
	s_cbranch_vccnz .LBB0_205
	s_ashr_i32 s37, s64, 31
	s_lshr_b32 s37, s37, 29
	s_add_i32 s37, s64, s37
	s_ashr_i32 s60, s37, 3
	s_and_b32 s37, s37, -8
	s_sub_i32 s37, s64, s37
	s_cmp_lt_i32 s37, 0
	s_movk_i32 s61, 0x141
	s_cselect_b32 s61, s61, 0x140
	s_mul_i32 s37, s61, s37
	s_add_i32 s37, s37, s60
	s_mul_hi_i32 s60, s37, 0x66666667
	s_lshr_b32 s61, s60, 31
	s_ashr_i32 s60, s60, 6
	s_add_i32 s60, s60, s61
	s_lshl_b32 s61, s60, 3
	s_sub_i32 s62, 0x80, s61
	s_min_i32 s62, s62, 8
	s_abs_i32 s63, s62
	s_sub_i32 s65, 0, s63
	s_mulk_i32 s60, 0xa0
	s_sub_i32 s37, s37, s60
	s_abs_i32 s60, s37
	s_xor_b32 s64, s37, s62
	s_ashr_i32 s64, s64, 31
	s_mov_b32 s70, 0x1fffffc0
	s_mul_i32 s65, s65, s70
	s_mul_hi_u32 s65, s70, s65
	s_add_i32 s70, s70, s65
	s_mul_hi_u32 s65, s60, s70
	s_mul_i32 s70, s65, s63
	s_sub_i32 s60, s60, s70
	s_add_i32 s71, s65, 1
	s_sub_i32 s70, s60, s63
	s_cmp_ge_u32 s60, s63
	s_cselect_b32 s65, s71, s65
	s_cselect_b32 s60, s70, s60
	s_add_i32 s70, s65, 1
	s_cmp_ge_u32 s60, s63
	s_cselect_b32 s60, s70, s65
	s_xor_b32 s60, s60, s64
	s_sub_i32 s60, s60, s64
	s_mul_i32 s62, s60, s62
	s_sub_i32 s37, s37, s62
	s_add_i32 s62, s37, s61

.LBB0_551:
	s_ashr_i32 s12, s14, 3
	s_add_i32 s12, s34, s12
	s_ashr_i32 s13, s12, 31
	s_lshr_b32 s13, s13, 27
	s_add_i32 s13, s12, s13
	s_ashr_i32 s14, s13, 5
	s_lshl_b32 s14, s14, 3
	s_sub_i32 s15, 0x80, s14
	s_min_i32 s15, s15, 8
	s_abs_i32 s34, s15
	s_sub_i32 s36, 0, s34
	s_andn2_b32 s13, s13, 31
	s_sub_i32 s13, s12, s13
	s_abs_i32 s12, s13
	s_xor_b32 s35, s13, s15
	s_ashr_i32 s35, s35, 31
	s_mov_b32 s37, 0x1fffffc0
	s_mul_i32 s36, s36, s37
	s_mul_hi_u32 s36, s37, s36
	s_add_i32 s37, s37, s36
	s_mul_hi_u32 s36, s12, s37
	s_mul_i32 s37, s36, s34
	s_sub_i32 s12, s12, s37
	s_add_i32 s70, s36, 1
	s_sub_i32 s37, s12, s34
	s_cmp_ge_u32 s12, s34
	s_cselect_b32 s36, s70, s36
	s_cselect_b32 s12, s37, s12
	s_add_i32 s37, s36, 1
	s_cmp_ge_u32 s12, s34
	s_cselect_b32 s12, s37, s36
	s_xor_b32 s12, s12, s35
	s_sub_i32 s12, s12, s35
	s_mul_i32 s15, s12, s15
	s_sub_i32 s13, s13, s15
	s_add_i32 s14, s14, s13

.LBB0_575:
	s_ashr_i32 s34, s36, 3
	s_add_i32 s34, s60, s34
	s_ashr_i32 s35, s34, 31
	s_lshr_b32 s35, s35, 27
	s_add_i32 s35, s34, s35
	s_ashr_i32 s36, s35, 5
	s_lshl_b32 s36, s36, 3
	s_sub_i32 s37, 0x80, s36
	s_min_i32 s37, s37, 8
	s_abs_i32 s60, s37
	s_sub_i32 s62, 0, s60
	s_andn2_b32 s35, s35, 31
	s_sub_i32 s35, s34, s35
	s_abs_i32 s34, s35
	s_xor_b32 s61, s35, s37
	s_ashr_i32 s61, s61, 31
	s_mov_b32 s63, 0x1fffffc0
	s_mul_i32 s62, s62, s63
	s_mul_hi_u32 s62, s63, s62
	s_add_i32 s63, s63, s62
	s_mul_hi_u32 s62, s34, s63
	s_mul_i32 s63, s62, s60
	s_sub_i32 s34, s34, s63
	s_add_i32 s74, s62, 1
	s_sub_i32 s63, s34, s60
	s_cmp_ge_u32 s34, s60
	s_cselect_b32 s62, s74, s62
	s_cselect_b32 s34, s63, s34
	s_add_i32 s63, s62, 1
	s_cmp_ge_u32 s34, s60
	s_cselect_b32 s34, s63, s62
	s_xor_b32 s34, s34, s61
	s_sub_i32 s34, s34, s61
	s_mul_i32 s37, s34, s37
	s_sub_i32 s35, s35, s37
	s_add_i32 s36, s36, s35

.LBB0_651:
	s_ashr_i32 s10, s10, 3
	s_add_i32 s10, s70, s10
	s_ashr_i32 s11, s10, 31
	s_lshr_b32 s11, s11, 27
	s_add_i32 s11, s10, s11
	s_ashr_i32 s12, s11, 5
	s_lshl_b32 s12, s12, 3
	s_sub_i32 s13, 0x80, s12
	s_min_i32 s13, s13, 8
	s_abs_i32 s66, s13
	s_sub_i32 s70, 0, s66
	s_andn2_b32 s11, s11, 31
	s_sub_i32 s10, s10, s11
	s_abs_i32 s11, s10
	s_xor_b32 s67, s10, s13
	s_ashr_i32 s67, s67, 31
	s_mov_b32 s80, 0x1fffffc0
	s_mul_i32 s70, s70, s80
	s_mul_hi_u32 s70, s80, s70
	s_add_i32 s80, s80, s70
	s_mul_hi_u32 s70, s11, s80
	s_mul_i32 s80, s70, s66
	s_sub_i32 s11, s11, s80
	s_add_i32 s81, s70, 1
	s_sub_i32 s80, s11, s66
	s_cmp_ge_u32 s11, s66
	s_cselect_b32 s70, s81, s70
	s_cselect_b32 s11, s80, s11
	s_add_i32 s80, s70, 1
	s_cmp_ge_u32 s11, s66
	s_cselect_b32 s11, s80, s70
	s_xor_b32 s11, s11, s67
	s_sub_i32 s80, s11, s67
	s_mul_i32 s11, s80, s13
	s_sub_i32 s10, s10, s11
	s_add_i32 s82, s12, s10

.LBB0_731:
	v_cmp_gt_i64_e32 vcc, s[0:1], v[0:1]
	s_mov_b32 s64, s13
	s_mov_b32 s65, s12
	s_mov_b32 s66, s11
	s_mov_b32 s6, s9
	s_mov_b32 s8, s10
	s_mov_b64 s[4:5], -1
	s_and_b64 vcc, exec, vcc
	s_cbranch_vccnz .LBB0_730
	s_ashr_i32 s4, s0, 31
	s_lshr_b32 s4, s4, 29
	s_add_i32 s4, s0, s4
	s_ashr_i32 s5, s4, 3
	s_and_b32 s4, s4, -8
	s_sub_i32 s4, s0, s4
	s_cmp_lt_i32 s4, 0
	s_cselect_b32 s9, s7, 0x160
	s_mul_i32 s4, s9, s4
	s_add_i32 s4, s4, s5
	s_mul_hi_i32 s5, s4, 0x2e8ba2e9
	s_lshr_b32 s9, s5, 31
	s_ashr_i32 s5, s5, 5
	s_add_i32 s5, s5, s9
	s_lshl_b32 s9, s5, 3
	s_sub_i32 s10, 0x80, s9
	s_min_i32 s10, s10, 8
	s_abs_i32 s10, s10
	s_sub_i32 s11, 0, s10
	s_mulk_i32 s5, 0xb0
	s_sub_i32 s4, s4, s5
	s_ashr_i32 s5, s4, 31
	s_abs_i32 s4, s4
	s_mov_b32 s12, 0x1fffffc0
	s_mul_i32 s11, s11, s12
	s_mul_hi_u32 s11, s12, s11
	s_add_i32 s12, s12, s11
	s_mul_hi_u32 s11, s4, s12
	s_mul_i32 s11, s11, s10
	s_sub_i32 s4, s4, s11
	s_sub_i32 s11, s4, s10
	s_cmp_ge_u32 s4, s10
	s_cselect_b32 s4, s11, s4
	s_sub_i32 s11, s4, s10
	s_cmp_ge_u32 s4, s10
	s_cselect_b32 s4, s11, s4
	s_xor_b32 s4, s4, s5
	s_sub_i32 s4, s4, s5
	s_add_i32 s4, s4, s9
	s_cmp_eq_u32 s4, s64
	s_cselect_b64 s[10:11], -1, 0
	s_cmp_eq_u32 s4, s65
	s_cselect_b64 s[12:13], -1, 0
	s_or_b64 s[10:11], s[10:11], s[12:13]
	s_cmp_eq_u32 s4, s66
	s_cselect_b64 s[12:13], -1, 0
	s_or_b64 s[10:11], s[10:11], s[12:13]
	s_cmp_eq_u32 s4, s6
	s_cselect_b64 s[12:13], -1, 0
	s_or_b64 s[10:11], s[10:11], s[12:13]
	s_andn2_b64 vcc, exec, s[10:11]
	s_mov_b32 s10, s8
	s_mov_b32 s9, s6
	s_mov_b32 s11, s66
	s_mov_b32 s12, s65
	s_mov_b32 s13, s64
	s_cbranch_vccz .LBB0_729
	s_cmp_eq_u32 s8, 3
	s_cselect_b32 s9, s4, s6
	s_cmp_eq_u32 s8, 2
	s_cselect_b32 s11, s4, s66
	s_cmp_eq_u32 s8, 1
	s_cselect_b32 s12, s4, s65
	s_cmp_eq_u32 s8, 0
	s_cselect_b32 s13, s4, s64
	s_add_i32 s10, s8, 1
	s_branch .LBB0_729

.LBB0_743:
	s_add_i32 s72, s72, 1
	s_mul_i32 s8, s72, s33
	s_mul_hi_u32 s9, s72, s38
	s_add_i32 s9, s9, s8
	s_mul_i32 s8, s72, s38
	s_add_u32 s36, s8, s2
	s_addc_u32 s37, s9, s3
	v_cmp_gt_i64_e32 vcc, s[36:37], v[182:183]
	v_cmp_lt_i64_e64 s[8:9], s[36:37], v[180:181]
	s_cbranch_vccnz .LBB0_745
	s_ashr_i32 s14, s36, 31
	s_lshr_b32 s14, s14, 29
	s_add_i32 s14, s36, s14
	s_ashr_i32 s15, s14, 3
	s_and_b32 s14, s14, -8
	s_sub_i32 s14, s36, s14
	s_cmp_lt_i32 s14, 0
	s_cselect_b32 s34, s68, 0x160
	s_mul_i32 s14, s34, s14
	s_add_i32 s14, s14, s15
	s_mul_hi_i32 s15, s14, 0x2e8ba2e9
	s_lshr_b32 s34, s15, 31
	s_ashr_i32 s15, s15, 5
	s_add_i32 s15, s15, s34
	s_lshl_b32 s34, s15, 3
	s_sub_i32 s35, 0x80, s34
	s_min_i32 s35, s35, 8
	s_abs_i32 s36, s35
	s_sub_i32 s40, 0, s36
	s_mulk_i32 s15, 0xb0
	s_sub_i32 s15, s14, s15
	s_abs_i32 s14, s15
	s_xor_b32 s37, s15, s35
	s_ashr_i32 s37, s37, 31
	s_mov_b32 s41, 0x1fffffc0
	s_mul_i32 s40, s40, s41
	s_mul_hi_u32 s40, s41, s40
	s_add_i32 s41, s41, s40
	s_mul_hi_u32 s40, s14, s41
	s_mul_i32 s41, s40, s36
	s_sub_i32 s14, s14, s41
	s_add_i32 s76, s40, 1
	s_sub_i32 s41, s14, s36
	s_cmp_ge_u32 s14, s36
	s_cselect_b32 s40, s76, s40
	s_cselect_b32 s14, s41, s14
	s_add_i32 s41, s40, 1
	s_cmp_ge_u32 s14, s36
	s_cselect_b32 s14, s41, s40
	s_xor_b32 s14, s14, s37
	s_sub_i32 s14, s14, s37
	s_mul_i32 s35, s14, s35
	s_sub_i32 s15, s15, s35
	s_add_i32 s34, s15, s34

.LBB0_824:
	s_ashr_i32 s8, s36, 3
	s_add_i32 s8, s46, s8
	s_ashr_i32 s9, s8, 31
	s_lshr_b32 s9, s9, 27
	s_add_i32 s9, s8, s9
	s_ashr_i32 s36, s9, 5
	s_lshl_b32 s36, s36, 3
	s_sub_i32 s37, 0x80, s36
	s_min_i32 s37, s37, 8
	s_abs_i32 s46, s37
	s_sub_i32 s73, 0, s46
	s_andn2_b32 s9, s9, 31
	s_sub_i32 s8, s8, s9
	s_abs_i32 s9, s8
	s_xor_b32 s47, s8, s37
	s_ashr_i32 s47, s47, 31
	s_mov_b32 s74, 0x1fffffc0
	s_mul_i32 s73, s73, s74
	s_mul_hi_u32 s73, s74, s73
	s_add_i32 s74, s74, s73
	s_mul_hi_u32 s73, s9, s74
	s_mul_i32 s74, s73, s46
	s_sub_i32 s9, s9, s74
	s_add_i32 s75, s73, 1
	s_sub_i32 s74, s9, s46
	s_cmp_ge_u32 s9, s46
	s_cselect_b32 s73, s75, s73
	s_cselect_b32 s9, s74, s9
	s_add_i32 s74, s73, 1
	s_cmp_ge_u32 s9, s46
	s_cselect_b32 s9, s74, s73
	s_xor_b32 s9, s9, s47
	s_sub_i32 s73, s9, s47
	s_mul_i32 s9, s73, s37
	s_sub_i32 s8, s8, s9
	s_add_i32 s78, s36, s8

.LBB0_1049:
	v_cmp_gt_i64_e32 vcc, s[0:1], v[0:1]
	s_mov_b32 s35, s12
	s_mov_b32 s68, s11
	s_mov_b32 s69, s10
	s_mov_b32 s6, s9
	s_mov_b32 s7, s8
	s_mov_b64 s[4:5], -1
	s_and_b64 vcc, exec, vcc
	s_cbranch_vccnz .LBB0_1048
	s_ashr_i32 s4, s0, 31
	s_lshr_b32 s4, s4, 29
	s_add_i32 s4, s0, s4
	s_ashr_i32 s5, s4, 3
	s_and_b32 s4, s4, -8
	s_sub_i32 s4, s0, s4
	s_cmp_lt_i32 s4, 0
	s_movk_i32 s8, 0x141
	s_cselect_b32 s8, s8, 0x140
	s_mul_i32 s4, s8, s4
	s_add_i32 s4, s4, s5
	s_mul_hi_i32 s5, s4, 0x66666667
	s_lshr_b32 s8, s5, 31
	s_ashr_i32 s5, s5, 6
	s_add_i32 s5, s5, s8
	s_lshl_b32 s8, s5, 3
	s_sub_i32 s9, 0x80, s8
	s_min_i32 s9, s9, 8
	s_abs_i32 s9, s9
	s_sub_i32 s10, 0, s9
	s_mulk_i32 s5, 0xa0
	s_sub_i32 s4, s4, s5
	s_ashr_i32 s5, s4, 31
	s_abs_i32 s4, s4
	s_mov_b32 s12, s35
	s_mov_b32 s11, 0x1fffffc0
	s_mul_i32 s10, s10, s11
	s_mul_hi_u32 s10, s11, s10
	s_add_i32 s11, s11, s10
	s_mul_hi_u32 s10, s4, s11
	s_mul_i32 s10, s10, s9
	s_sub_i32 s4, s4, s10
	s_sub_i32 s10, s4, s9
	s_cmp_ge_u32 s4, s9
	s_cselect_b32 s4, s10, s4
	s_sub_i32 s10, s4, s9
	s_cmp_ge_u32 s4, s9
	s_cselect_b32 s4, s10, s4
	s_xor_b32 s4, s4, s5
	s_sub_i32 s4, s4, s5
	s_add_i32 s4, s4, s8
	s_cmp_eq_u32 s4, s35
	s_cselect_b64 s[8:9], -1, 0
	s_cmp_eq_u32 s4, s68
	s_cselect_b64 s[10:11], -1, 0
	s_or_b64 s[8:9], s[8:9], s[10:11]
	s_cmp_eq_u32 s4, s69
	s_cselect_b64 s[10:11], -1, 0
	s_or_b64 s[8:9], s[8:9], s[10:11]
	s_cmp_eq_u32 s4, s6
	s_cselect_b64 s[10:11], -1, 0
	s_or_b64 s[8:9], s[8:9], s[10:11]
	s_andn2_b64 vcc, exec, s[8:9]
	s_mov_b32 s8, s7
	s_mov_b32 s9, s6
	s_mov_b32 s10, s69
	s_mov_b32 s11, s68
	s_cbranch_vccz .LBB0_1047
	s_cmp_eq_u32 s7, 3
	s_cselect_b32 s9, s4, s6
	s_cmp_eq_u32 s7, 2
	s_cselect_b32 s10, s4, s69
	s_cmp_eq_u32 s7, 1
	s_cselect_b32 s11, s4, s68
	s_cmp_eq_u32 s7, 0
	s_cselect_b32 s12, s4, s35
	s_add_i32 s8, s7, 1
	s_branch .LBB0_1047

.LBB0_1411:
	s_ashr_i32 s10, s12, 3
	s_add_i32 s10, s14, s10
	s_ashr_i32 s11, s10, 31
	s_lshr_b32 s11, s11, 27
	s_add_i32 s11, s10, s11
	s_ashr_i32 s12, s11, 5
	s_lshl_b32 s12, s12, 3
	s_sub_i32 s13, 0x80, s12
	s_min_i32 s13, s13, 8
	s_abs_i32 s14, s13
	s_sub_i32 s34, 0, s14
	s_andn2_b32 s11, s11, 31
	s_sub_i32 s11, s10, s11
	s_abs_i32 s10, s11
	s_xor_b32 s15, s11, s13
	s_ashr_i32 s15, s15, 31
	s_mov_b32 s35, 0x1fffffc0
	s_mul_i32 s34, s34, s35
	s_mul_hi_u32 s34, s35, s34
	s_add_i32 s35, s35, s34
	s_mul_hi_u32 s34, s10, s35
	s_mul_i32 s35, s34, s14
	s_sub_i32 s10, s10, s35
	s_add_i32 s60, s34, 1
	s_sub_i32 s35, s10, s14
	s_cmp_ge_u32 s10, s14
	s_cselect_b32 s34, s60, s34
	s_cselect_b32 s10, s35, s10
	s_add_i32 s35, s34, 1
	s_cmp_ge_u32 s10, s14
	s_cselect_b32 s10, s35, s34
	s_xor_b32 s10, s10, s15
	s_sub_i32 s10, s10, s15
	s_mul_i32 s13, s10, s13
	s_sub_i32 s11, s11, s13
	s_add_i32 s12, s12, s11

.LBB0_1435:
	s_ashr_i32 s34, s36, 3
	s_add_i32 s34, s40, s34
	s_ashr_i32 s35, s34, 31
	s_lshr_b32 s35, s35, 27
	s_add_i32 s35, s34, s35
	s_ashr_i32 s36, s35, 5
	s_lshl_b32 s36, s36, 3
	s_sub_i32 s37, 0x80, s36
	s_min_i32 s37, s37, 8
	s_abs_i32 s40, s37
	s_sub_i32 s60, 0, s40
	s_andn2_b32 s35, s35, 31
	s_sub_i32 s35, s34, s35
	s_abs_i32 s34, s35
	s_xor_b32 s41, s35, s37
	s_ashr_i32 s41, s41, 31
	s_mov_b32 s61, 0x1fffffc0
	s_mul_i32 s60, s60, s61
	s_mul_hi_u32 s60, s61, s60
	s_add_i32 s61, s61, s60
	s_mul_hi_u32 s60, s34, s61
	s_mul_i32 s61, s60, s40
	s_sub_i32 s34, s34, s61
	s_add_i32 s85, s60, 1
	s_sub_i32 s61, s34, s40
	s_cmp_ge_u32 s34, s40
	s_cselect_b32 s60, s85, s60
	s_cselect_b32 s34, s61, s34
	s_add_i32 s61, s60, 1
	s_cmp_ge_u32 s34, s40
	s_cselect_b32 s34, s61, s60
	s_xor_b32 s34, s34, s41
	s_sub_i32 s34, s34, s41
	s_mul_i32 s37, s34, s37
	s_sub_i32 s35, s35, s37
	s_add_i32 s36, s36, s35

.LBB0_1511:
	s_ashr_i32 s34, s36, 3
	s_add_i32 s34, s46, s34
	s_ashr_i32 s35, s34, 31
	s_lshr_b32 s35, s35, 27
	s_add_i32 s35, s34, s35
	s_ashr_i32 s36, s35, 5
	s_lshl_b32 s36, s36, 3
	s_sub_i32 s37, 0x80, s36
	s_min_i32 s37, s37, 8
	s_abs_i32 s46, s37
	s_sub_i32 s60, 0, s46
	s_andn2_b32 s35, s35, 31
	s_sub_i32 s35, s34, s35
	s_abs_i32 s34, s35
	s_xor_b32 s47, s35, s37
	s_ashr_i32 s47, s47, 31
	s_mov_b32 s61, 0x1fffffc0
	s_mul_i32 s60, s60, s61
	s_mul_hi_u32 s60, s61, s60
	s_add_i32 s61, s61, s60
	s_mul_hi_u32 s60, s34, s61
	s_mul_i32 s61, s60, s46
	s_sub_i32 s34, s34, s61
	s_add_i32 s73, s60, 1
	s_sub_i32 s61, s34, s46
	s_cmp_ge_u32 s34, s46
	s_cselect_b32 s60, s73, s60
	s_cselect_b32 s34, s61, s34
	s_add_i32 s61, s60, 1
	s_cmp_ge_u32 s34, s46
	s_cselect_b32 s34, s61, s60
	s_xor_b32 s34, s34, s47
	s_sub_i32 s34, s34, s47
	s_mul_i32 s37, s34, s37
	s_sub_i32 s35, s35, s37
	s_add_i32 s36, s36, s35

.LBB0_1591:
	v_cmp_gt_i64_e32 vcc, s[0:1], v[0:1]
	s_mov_b32 s64, s12
	s_mov_b32 s65, s11
	s_mov_b32 s66, s10
	s_mov_b32 s6, s9
	s_mov_b32 s7, s8
	s_mov_b64 s[4:5], -1
	s_and_b64 vcc, exec, vcc
	s_cbranch_vccnz .LBB0_1590
	s_ashr_i32 s4, s0, 31
	s_lshr_b32 s4, s4, 29
	s_add_i32 s4, s0, s4
	s_ashr_i32 s5, s4, 3
	s_and_b32 s4, s4, -8
	s_sub_i32 s4, s0, s4
	s_cmp_lt_i32 s4, 0
	s_movk_i32 s8, 0x161
	s_cselect_b32 s8, s8, 0x160
	s_mul_i32 s4, s8, s4
	s_add_i32 s4, s4, s5
	s_mul_hi_i32 s5, s4, 0x2e8ba2e9
	s_lshr_b32 s8, s5, 31
	s_ashr_i32 s5, s5, 5
	s_add_i32 s5, s5, s8
	s_lshl_b32 s8, s5, 3
	s_sub_i32 s9, 0x80, s8
	s_min_i32 s9, s9, 8
	s_abs_i32 s9, s9
	s_sub_i32 s10, 0, s9
	s_mulk_i32 s5, 0xb0
	s_sub_i32 s4, s4, s5
	s_ashr_i32 s5, s4, 31
	s_abs_i32 s4, s4
	s_mov_b32 s12, s64
	s_mov_b32 s11, 0x1fffffc0
	s_mul_i32 s10, s10, s11
	s_mul_hi_u32 s10, s11, s10
	s_add_i32 s11, s11, s10
	s_mul_hi_u32 s10, s4, s11
	s_mul_i32 s10, s10, s9
	s_sub_i32 s4, s4, s10
	s_sub_i32 s10, s4, s9
	s_cmp_ge_u32 s4, s9
	s_cselect_b32 s4, s10, s4
	s_sub_i32 s10, s4, s9
	s_cmp_ge_u32 s4, s9
	s_cselect_b32 s4, s10, s4
	s_xor_b32 s4, s4, s5
	s_sub_i32 s4, s4, s5
	s_add_i32 s4, s4, s8
	s_cmp_eq_u32 s4, s64
	s_cselect_b64 s[8:9], -1, 0
	s_cmp_eq_u32 s4, s65
	s_cselect_b64 s[10:11], -1, 0
	s_or_b64 s[8:9], s[8:9], s[10:11]
	s_cmp_eq_u32 s4, s66
	s_cselect_b64 s[10:11], -1, 0
	s_or_b64 s[8:9], s[8:9], s[10:11]
	s_cmp_eq_u32 s4, s6
	s_cselect_b64 s[10:11], -1, 0
	s_or_b64 s[8:9], s[8:9], s[10:11]
	s_andn2_b64 vcc, exec, s[8:9]
	s_mov_b32 s8, s7
	s_mov_b32 s9, s6
	s_mov_b32 s10, s66
	s_mov_b32 s11, s65
	s_cbranch_vccz .LBB0_1589
	s_cmp_eq_u32 s7, 3
	s_cselect_b32 s9, s4, s6
	s_cmp_eq_u32 s7, 2
	s_cselect_b32 s10, s4, s66
	s_cmp_eq_u32 s7, 1
	s_cselect_b32 s11, s4, s65
	s_cmp_eq_u32 s7, 0
	s_cselect_b32 s12, s4, s64
	s_add_i32 s8, s7, 1
	s_branch .LBB0_1589

.LBB0_1603:
	s_add_i32 s73, s73, 1
	s_mul_i32 s10, s73, s33
	s_mul_hi_u32 s11, s73, s38
	s_add_i32 s11, s11, s10
	s_mul_i32 s10, s73, s38
	s_add_u32 s36, s10, s2
	s_addc_u32 s37, s11, s3
	v_cmp_gt_i64_e32 vcc, s[36:37], v[182:183]
	v_cmp_lt_i64_e64 s[10:11], s[36:37], v[180:181]
	s_cbranch_vccnz .LBB0_1605
	s_ashr_i32 s14, s36, 31
	s_lshr_b32 s14, s14, 29
	s_add_i32 s14, s36, s14
	s_ashr_i32 s15, s14, 3
	s_and_b32 s14, s14, -8
	s_sub_i32 s14, s36, s14
	s_cmp_lt_i32 s14, 0
	s_cselect_b32 s34, s68, 0x160
	s_mul_i32 s14, s34, s14
	s_add_i32 s14, s14, s15
	s_mul_hi_i32 s15, s14, 0x2e8ba2e9
	s_lshr_b32 s34, s15, 31
	s_ashr_i32 s15, s15, 5
	s_add_i32 s15, s15, s34
	s_lshl_b32 s34, s15, 3
	s_sub_i32 s35, 0x80, s34
	s_min_i32 s35, s35, 8
	s_abs_i32 s36, s35
	s_sub_i32 s60, 0, s36
	s_mulk_i32 s15, 0xb0
	s_sub_i32 s15, s14, s15
	s_abs_i32 s14, s15
	s_xor_b32 s37, s15, s35
	s_ashr_i32 s37, s37, 31
	s_mov_b32 s61, 0x1fffffc0
	s_mul_i32 s60, s60, s61
	s_mul_hi_u32 s60, s61, s60
	s_add_i32 s61, s61, s60
	s_mul_hi_u32 s60, s14, s61
	s_mul_i32 s61, s60, s36
	s_sub_i32 s14, s14, s61
	s_add_i32 s82, s60, 1
	s_sub_i32 s61, s14, s36
	s_cmp_ge_u32 s14, s36
	s_cselect_b32 s60, s82, s60
	s_cselect_b32 s14, s61, s14
	s_add_i32 s61, s60, 1
	s_cmp_ge_u32 s14, s36
	s_cselect_b32 s14, s61, s60
	s_xor_b32 s14, s14, s37
	s_sub_i32 s14, s14, s37
	s_mul_i32 s35, s14, s35
	s_sub_i32 s15, s15, s35
	s_add_i32 s34, s15, s34

.LBB0_1684:
	s_ashr_i32 s10, s46, 3
	s_add_i32 s10, s60, s10
	s_ashr_i32 s11, s10, 31
	s_lshr_b32 s11, s11, 27
	s_add_i32 s11, s10, s11
	s_ashr_i32 s46, s11, 5
	s_lshl_b32 s46, s46, 3
	s_sub_i32 s47, 0x80, s46
	s_min_i32 s47, s47, 8
	s_abs_i32 s60, s47
	s_sub_i32 s73, 0, s60
	s_andn2_b32 s11, s11, 31
	s_sub_i32 s10, s10, s11
	s_abs_i32 s11, s10
	s_xor_b32 s61, s10, s47
	s_ashr_i32 s61, s61, 31
	s_mov_b32 s78, 0x1fffffc0
	s_mul_i32 s73, s73, s78
	s_mul_hi_u32 s73, s78, s73
	s_add_i32 s78, s78, s73
	s_mul_hi_u32 s73, s11, s78
	s_mul_i32 s78, s73, s60
	s_sub_i32 s11, s11, s78
	s_add_i32 s81, s73, 1
	s_sub_i32 s78, s11, s60
	s_cmp_ge_u32 s11, s60
	s_cselect_b32 s73, s81, s73
	s_cselect_b32 s11, s78, s11
	s_add_i32 s78, s73, 1
	s_cmp_ge_u32 s11, s60
	s_cselect_b32 s11, s78, s73
	s_xor_b32 s11, s11, s61
	s_sub_i32 s73, s11, s61
	s_mul_i32 s11, s73, s47
	s_sub_i32 s10, s10, s11
	s_add_i32 s78, s46, s10

.LBB0_2272:
	s_ashr_i32 s8, s12, 3
	s_add_i32 s8, s14, s8
	s_ashr_i32 s9, s8, 31
	s_lshr_b32 s9, s9, 27
	s_add_i32 s9, s8, s9
	s_ashr_i32 s12, s9, 5
	s_lshl_b32 s12, s12, 3
	s_sub_i32 s13, 0x80, s12
	s_min_i32 s13, s13, 8
	s_abs_i32 s14, s13
	s_sub_i32 s34, 0, s14
	s_andn2_b32 s9, s9, 31
	s_sub_i32 s9, s8, s9
	s_abs_i32 s8, s9
	s_xor_b32 s15, s9, s13
	s_ashr_i32 s15, s15, 31
	s_mov_b32 s35, 0x1fffffc0
	s_mul_i32 s34, s34, s35
	s_mul_hi_u32 s34, s35, s34
	s_add_i32 s35, s35, s34
	s_mul_hi_u32 s34, s8, s35
	s_mul_i32 s35, s34, s14
	s_sub_i32 s8, s8, s35
	s_add_i32 s60, s34, 1
	s_sub_i32 s35, s8, s14
	s_cmp_ge_u32 s8, s14
	s_cselect_b32 s34, s60, s34
	s_cselect_b32 s8, s35, s8
	s_add_i32 s35, s34, 1
	s_cmp_ge_u32 s8, s14
	s_cselect_b32 s8, s35, s34
	s_xor_b32 s8, s8, s15
	s_sub_i32 s8, s8, s15
	s_mul_i32 s13, s8, s13
	s_sub_i32 s9, s9, s13
	s_add_i32 s12, s12, s9

.LBB0_2372:
	s_ashr_i32 s36, s47, 3
	s_add_i32 s36, s60, s36
	s_ashr_i32 s37, s36, 31
	s_lshr_b32 s37, s37, 27
	s_add_i32 s37, s36, s37
	s_ashr_i32 s46, s37, 5
	s_lshl_b32 s46, s46, 3
	s_sub_i32 s47, 0x80, s46
	s_min_i32 s47, s47, 8
	s_abs_i32 s60, s47
	s_sub_i32 s73, 0, s60
	s_andn2_b32 s37, s37, 31
	s_sub_i32 s37, s36, s37
	s_abs_i32 s36, s37
	s_xor_b32 s61, s37, s47
	s_ashr_i32 s61, s61, 31
	s_mov_b32 s78, 0x1fffffc0
	s_mul_i32 s73, s73, s78
	s_mul_hi_u32 s73, s78, s73
	s_add_i32 s78, s78, s73
	s_mul_hi_u32 s73, s36, s78
	s_mul_i32 s78, s73, s60
	s_sub_i32 s36, s36, s78
	s_add_i32 s79, s73, 1
	s_sub_i32 s78, s36, s60
	s_cmp_ge_u32 s36, s60
	s_cselect_b32 s73, s79, s73
	s_cselect_b32 s36, s78, s36
	s_add_i32 s78, s73, 1
	s_cmp_ge_u32 s36, s60
	s_cselect_b32 s36, s78, s73
	s_xor_b32 s36, s36, s61
	s_sub_i32 s36, s36, s61
	s_mul_i32 s47, s36, s47
	s_sub_i32 s37, s37, s47
	s_add_i32 s60, s46, s37

.LBB0_2773:
	v_cmp_gt_i64_e32 vcc, s[0:1], v[0:1]
	s_mov_b32 s19, s13
	s_mov_b32 s60, s12
	s_mov_b32 s61, s11
	s_mov_b32 s6, s9
	s_mov_b32 s8, s10
	s_mov_b64 s[4:5], -1
	s_and_b64 vcc, exec, vcc
	s_cbranch_vccnz .LBB0_2772
	s_ashr_i32 s4, s0, 31
	s_lshr_b32 s4, s4, 29
	s_add_i32 s4, s0, s4
	s_ashr_i32 s5, s4, 3
	s_and_b32 s4, s4, -8
	s_sub_i32 s4, s0, s4
	s_cmp_lt_i32 s4, 0
	s_cselect_b32 s9, s7, 0x140
	s_mul_i32 s4, s9, s4
	s_add_i32 s4, s4, s5
	s_mul_hi_i32 s5, s4, 0x66666667
	s_lshr_b32 s9, s5, 31
	s_ashr_i32 s5, s5, 6
	s_add_i32 s5, s5, s9
	s_lshl_b32 s9, s5, 3
	s_sub_i32 s10, 0x80, s9
	s_min_i32 s10, s10, 8
	s_abs_i32 s10, s10
	s_sub_i32 s11, 0, s10
	s_mulk_i32 s5, 0xa0
	s_sub_i32 s4, s4, s5
	s_ashr_i32 s5, s4, 31
	s_abs_i32 s4, s4
	s_mov_b32 s12, 0x1fffffc0
	s_mul_i32 s11, s11, s12
	s_mul_hi_u32 s11, s12, s11
	s_add_i32 s12, s12, s11
	s_mul_hi_u32 s11, s4, s12
	s_mul_i32 s11, s11, s10
	s_sub_i32 s4, s4, s11
	s_sub_i32 s11, s4, s10
	s_cmp_ge_u32 s4, s10
	s_cselect_b32 s4, s11, s4
	s_sub_i32 s11, s4, s10
	s_cmp_ge_u32 s4, s10
	s_cselect_b32 s4, s11, s4
	s_xor_b32 s4, s4, s5
	s_sub_i32 s4, s4, s5
	s_add_i32 s4, s4, s9
	s_cmp_eq_u32 s4, s19
	s_cselect_b64 s[10:11], -1, 0
	s_cmp_eq_u32 s4, s60
	s_cselect_b64 s[12:13], -1, 0
	s_or_b64 s[10:11], s[10:11], s[12:13]
	s_cmp_eq_u32 s4, s61
	s_cselect_b64 s[12:13], -1, 0
	s_or_b64 s[10:11], s[10:11], s[12:13]
	s_cmp_eq_u32 s4, s6
	s_cselect_b64 s[12:13], -1, 0
	s_or_b64 s[10:11], s[10:11], s[12:13]
	s_andn2_b64 vcc, exec, s[10:11]
	s_mov_b32 s10, s8
	s_mov_b32 s9, s6
	s_mov_b32 s11, s61
	s_mov_b32 s12, s60
	s_mov_b32 s13, s19
	s_cbranch_vccz .LBB0_2771
	s_cmp_eq_u32 s8, 3
	s_cselect_b32 s9, s4, s6
	s_cmp_eq_u32 s8, 2
	s_cselect_b32 s11, s4, s61
	s_cmp_eq_u32 s8, 1
	s_cselect_b32 s12, s4, s60
	s_cmp_eq_u32 s8, 0
	s_cselect_b32 s13, s4, s19
	s_add_i32 s10, s8, 1
	s_branch .LBB0_2771

.LBB0_2787:
	s_add_i32 s79, s79, 1
	s_mul_i32 s0, s79, s33
	s_mul_hi_u32 s10, s79, s38
	s_add_i32 s10, s10, s0
	s_mul_i32 s0, s79, s38
	s_add_u32 s26, s0, s2
	s_addc_u32 s27, s10, s3
	v_cmp_gt_i64_e32 vcc, s[26:27], v[190:191]
	v_cmp_lt_i64_e64 s[10:11], s[26:27], v[188:189]
	s_cbranch_vccnz .LBB0_2789
	s_ashr_i32 s0, s26, 31
	s_lshr_b32 s0, s0, 29
	s_add_i32 s0, s26, s0
	s_ashr_i32 s22, s0, 3
	s_and_b32 s0, s0, -8
	s_sub_i32 s0, s26, s0
	s_cmp_lt_i32 s0, 0
	s_movk_i32 s23, 0x141
	s_cselect_b32 s23, s23, 0x140
	s_mul_i32 s0, s23, s0
	s_add_i32 s0, s0, s22
	s_mul_hi_i32 s22, s0, 0x66666667
	s_lshr_b32 s23, s22, 31
	s_ashr_i32 s22, s22, 6
	s_add_i32 s22, s22, s23
	s_lshl_b32 s23, s22, 3
	s_sub_i32 s24, 0x80, s23
	s_min_i32 s24, s24, 8
	s_abs_i32 s25, s24
	s_sub_i32 s27, 0, s25
	s_mulk_i32 s22, 0xa0
	s_sub_i32 s0, s0, s22
	s_abs_i32 s22, s0
	s_xor_b32 s26, s0, s24
	s_ashr_i32 s26, s26, 31
	s_mov_b32 s34, 0x1fffffc0
	s_mul_i32 s27, s27, s34
	s_mul_hi_u32 s27, s34, s27
	s_add_i32 s34, s34, s27
	s_mul_hi_u32 s27, s22, s34
	s_mul_i32 s34, s27, s25
	s_sub_i32 s22, s22, s34
	s_add_i32 s35, s27, 1
	s_sub_i32 s34, s22, s25
	s_cmp_ge_u32 s22, s25
	s_cselect_b32 s27, s35, s27
	s_cselect_b32 s22, s34, s22
	s_add_i32 s34, s27, 1
	s_cmp_ge_u32 s22, s25
	s_cselect_b32 s22, s34, s27
	s_xor_b32 s22, s22, s26
	s_sub_i32 s22, s22, s26
	s_mul_i32 s24, s22, s24
	s_sub_i32 s0, s0, s24
	s_add_i32 s24, s0, s23

.LBB0_3136:
	s_ashr_i32 s10, s12, 3
	s_add_i32 s10, s16, s10
	s_ashr_i32 s11, s10, 31
	s_lshr_b32 s11, s11, 27
	s_add_i32 s11, s10, s11
	s_ashr_i32 s12, s11, 5
	s_lshl_b32 s12, s12, 3
	s_sub_i32 s13, 0x80, s12
	s_min_i32 s13, s13, 8
	s_abs_i32 s16, s13
	s_sub_i32 s18, 0, s16
	s_andn2_b32 s11, s11, 31
	s_sub_i32 s11, s10, s11
	s_abs_i32 s10, s11
	s_xor_b32 s17, s11, s13
	s_ashr_i32 s17, s17, 31
	s_mov_b32 s19, 0x1fffffc0
	s_mul_i32 s18, s18, s19
	s_mul_hi_u32 s18, s19, s18
	s_add_i32 s19, s19, s18
	s_mul_hi_u32 s18, s10, s19
	s_mul_i32 s19, s18, s16
	s_sub_i32 s10, s10, s19
	s_add_i32 s34, s18, 1
	s_sub_i32 s19, s10, s16
	s_cmp_ge_u32 s10, s16
	s_cselect_b32 s18, s34, s18
	s_cselect_b32 s10, s19, s10
	s_add_i32 s19, s18, 1
	s_cmp_ge_u32 s10, s16
	s_cselect_b32 s10, s19, s18
	s_xor_b32 s10, s10, s17
	s_sub_i32 s10, s10, s17
	s_mul_i32 s13, s10, s13
	s_sub_i32 s11, s11, s13
	s_add_i32 s12, s12, s11

.LBB0_3160:
	s_ashr_i32 s18, s22, 3
	s_add_i32 s18, s24, s18
	s_ashr_i32 s19, s18, 31
	s_lshr_b32 s19, s19, 27
	s_add_i32 s19, s18, s19
	s_ashr_i32 s22, s19, 5
	s_lshl_b32 s22, s22, 3
	s_sub_i32 s23, 0x80, s22
	s_min_i32 s23, s23, 8
	s_abs_i32 s24, s23
	s_sub_i32 s26, 0, s24
	s_andn2_b32 s19, s19, 31
	s_sub_i32 s19, s18, s19
	s_abs_i32 s18, s19
	s_xor_b32 s25, s19, s23
	s_ashr_i32 s25, s25, 31
	s_mov_b32 s27, 0x1fffffc0
	s_mul_i32 s26, s26, s27
	s_mul_hi_u32 s26, s27, s26
	s_add_i32 s27, s27, s26
	s_mul_hi_u32 s26, s18, s27
	s_mul_i32 s27, s26, s24
	s_sub_i32 s18, s18, s27
	s_add_i32 s46, s26, 1
	s_sub_i32 s27, s18, s24
	s_cmp_ge_u32 s18, s24
	s_cselect_b32 s26, s46, s26
	s_cselect_b32 s18, s27, s18
	s_add_i32 s27, s26, 1
	s_cmp_ge_u32 s18, s24
	s_cselect_b32 s18, s27, s26
	s_xor_b32 s18, s18, s25
	s_sub_i32 s18, s18, s25
	s_mul_i32 s23, s18, s23
	s_sub_i32 s19, s19, s23
	s_add_i32 s22, s22, s19

.LBB0_3236:
	s_ashr_i32 s22, s24, 3
	s_add_i32 s22, s26, s22
	s_ashr_i32 s23, s22, 31
	s_lshr_b32 s23, s23, 27
	s_add_i32 s23, s22, s23
	s_ashr_i32 s24, s23, 5
	s_lshl_b32 s24, s24, 3
	s_sub_i32 s25, 0x80, s24
	s_min_i32 s25, s25, 8
	s_abs_i32 s26, s25
	s_sub_i32 s34, 0, s26
	s_andn2_b32 s23, s23, 31
	s_sub_i32 s23, s22, s23
	s_abs_i32 s22, s23
	s_xor_b32 s27, s23, s25
	s_ashr_i32 s27, s27, 31
	s_mov_b32 s35, 0x1fffffc0
	s_mul_i32 s34, s34, s35
	s_mul_hi_u32 s34, s35, s34
	s_add_i32 s35, s35, s34
	s_mul_hi_u32 s34, s22, s35
	s_mul_i32 s35, s34, s26
	s_sub_i32 s22, s22, s35
	s_add_i32 s37, s34, 1
	s_sub_i32 s35, s22, s26
	s_cmp_ge_u32 s22, s26
	s_cselect_b32 s34, s37, s34
	s_cselect_b32 s22, s35, s22
	s_add_i32 s35, s34, 1
	s_cmp_ge_u32 s22, s26
	s_cselect_b32 s22, s35, s34
	s_xor_b32 s22, s22, s27
	s_sub_i32 s22, s22, s27
	s_mul_i32 s25, s22, s25
	s_sub_i32 s23, s23, s25
	s_add_i32 s24, s24, s23

.LBB0_3316:
	v_cmp_gt_i64_e32 vcc, s[0:1], v[0:1]
	s_mov_b32 s46, s13
	s_mov_b32 s47, s12
	s_mov_b32 s48, s11
	s_mov_b32 s6, s9
	s_mov_b32 s8, s10
	s_mov_b64 s[4:5], -1
	s_and_b64 vcc, exec, vcc
	s_cbranch_vccnz .LBB0_3315
	s_ashr_i32 s4, s0, 31
	s_lshr_b32 s4, s4, 29
	s_add_i32 s4, s0, s4
	s_ashr_i32 s5, s4, 3
	s_and_b32 s4, s4, -8
	s_sub_i32 s4, s0, s4
	s_cmp_lt_i32 s4, 0
	s_cselect_b32 s9, s7, 0x160
	s_mul_i32 s4, s9, s4
	s_add_i32 s4, s4, s5
	s_mul_hi_i32 s5, s4, 0x2e8ba2e9
	s_lshr_b32 s9, s5, 31
	s_ashr_i32 s5, s5, 5
	s_add_i32 s5, s5, s9
	s_lshl_b32 s9, s5, 3
	s_sub_i32 s10, 0x80, s9
	s_min_i32 s10, s10, 8
	s_abs_i32 s10, s10
	s_sub_i32 s11, 0, s10
	s_mulk_i32 s5, 0xb0
	s_sub_i32 s4, s4, s5
	s_ashr_i32 s5, s4, 31
	s_abs_i32 s4, s4
	s_mov_b32 s12, 0x1fffffc0
	s_mul_i32 s11, s11, s12
	s_mul_hi_u32 s11, s12, s11
	s_add_i32 s12, s12, s11
	s_mul_hi_u32 s11, s4, s12
	s_mul_i32 s11, s11, s10
	s_sub_i32 s4, s4, s11
	s_sub_i32 s11, s4, s10
	s_cmp_ge_u32 s4, s10
	s_cselect_b32 s4, s11, s4
	s_sub_i32 s11, s4, s10
	s_cmp_ge_u32 s4, s10
	s_cselect_b32 s4, s11, s4
	s_xor_b32 s4, s4, s5
	s_sub_i32 s4, s4, s5
	s_add_i32 s4, s4, s9
	s_cmp_eq_u32 s4, s46
	s_cselect_b64 s[10:11], -1, 0
	s_cmp_eq_u32 s4, s47
	s_cselect_b64 s[12:13], -1, 0
	s_or_b64 s[10:11], s[10:11], s[12:13]
	s_cmp_eq_u32 s4, s48
	s_cselect_b64 s[12:13], -1, 0
	s_or_b64 s[10:11], s[10:11], s[12:13]
	s_cmp_eq_u32 s4, s6
	s_cselect_b64 s[12:13], -1, 0
	s_or_b64 s[10:11], s[10:11], s[12:13]
	s_andn2_b64 vcc, exec, s[10:11]
	s_mov_b32 s10, s8
	s_mov_b32 s9, s6
	s_mov_b32 s11, s48
	s_mov_b32 s12, s47
	s_mov_b32 s13, s46
	s_cbranch_vccz .LBB0_3314
	s_cmp_eq_u32 s8, 3
	s_cselect_b32 s9, s4, s6
	s_cmp_eq_u32 s8, 2
	s_cselect_b32 s11, s4, s48
	s_cmp_eq_u32 s8, 1
	s_cselect_b32 s12, s4, s47
	s_cmp_eq_u32 s8, 0
	s_cselect_b32 s13, s4, s46
	s_add_i32 s10, s8, 1
	s_branch .LBB0_3314

.LBB0_3328:
	s_add_i32 s54, s54, 1
	s_mul_i32 s6, s54, s33
	s_mul_hi_u32 s7, s54, s38
	s_add_i32 s7, s7, s6
	s_mul_i32 s6, s54, s38
	s_add_u32 s22, s6, s2
	s_addc_u32 s23, s7, s3
	v_cmp_gt_i64_e32 vcc, s[22:23], v[174:175]
	v_cmp_lt_i64_e64 s[6:7], s[22:23], v[172:173]
	s_cbranch_vccnz .LBB0_3330
	s_ashr_i32 s16, s22, 31
	s_lshr_b32 s16, s16, 29
	s_add_i32 s16, s22, s16
	s_ashr_i32 s17, s16, 3
	s_and_b32 s16, s16, -8
	s_sub_i32 s16, s22, s16
	s_cmp_lt_i32 s16, 0
	s_cselect_b32 s18, s50, 0x160
	s_mul_i32 s16, s18, s16
	s_add_i32 s16, s16, s17
	s_mul_hi_i32 s17, s16, 0x2e8ba2e9
	s_lshr_b32 s18, s17, 31
	s_ashr_i32 s17, s17, 5
	s_add_i32 s17, s17, s18
	s_lshl_b32 s18, s17, 3
	s_sub_i32 s19, 0x80, s18
	s_min_i32 s19, s19, 8
	s_abs_i32 s22, s19
	s_sub_i32 s24, 0, s22
	s_mulk_i32 s17, 0xb0
	s_sub_i32 s17, s16, s17
	s_abs_i32 s16, s17
	s_xor_b32 s23, s17, s19
	s_ashr_i32 s23, s23, 31
	s_mov_b32 s25, 0x1fffffc0
	s_mul_i32 s24, s24, s25
	s_mul_hi_u32 s24, s25, s24
	s_add_i32 s25, s25, s24
	s_mul_hi_u32 s24, s16, s25
	s_mul_i32 s25, s24, s22
	s_sub_i32 s16, s16, s25
	s_add_i32 s40, s24, 1
	s_sub_i32 s25, s16, s22
	s_cmp_ge_u32 s16, s22
	s_cselect_b32 s24, s40, s24
	s_cselect_b32 s16, s25, s16
	s_add_i32 s25, s24, 1
	s_cmp_ge_u32 s16, s22
	s_cselect_b32 s16, s25, s24
	s_xor_b32 s16, s16, s23
	s_sub_i32 s16, s16, s23
	s_mul_i32 s19, s16, s19
	s_sub_i32 s17, s17, s19
	s_add_i32 s18, s17, s18

.LBB0_3409:
	s_ashr_i32 s4, s22, 3
	s_add_i32 s4, s34, s4
	s_ashr_i32 s5, s4, 31
	s_lshr_b32 s5, s5, 27
	s_add_i32 s5, s4, s5
	s_ashr_i32 s22, s5, 5
	s_lshl_b32 s22, s22, 3
	s_sub_i32 s23, 0x80, s22
	s_min_i32 s23, s23, 8
	s_abs_i32 s34, s23
	s_sub_i32 s36, 0, s34
	s_andn2_b32 s5, s5, 31
	s_sub_i32 s4, s4, s5
	s_abs_i32 s5, s4
	s_xor_b32 s35, s4, s23
	s_ashr_i32 s35, s35, 31
	s_mov_b32 s37, 0x1fffffc0
	s_mul_i32 s36, s36, s37
	s_mul_hi_u32 s36, s37, s36
	s_add_i32 s37, s37, s36
	s_mul_hi_u32 s36, s5, s37
	s_mul_i32 s37, s36, s34
	s_sub_i32 s5, s5, s37
	s_add_i32 s54, s36, 1
	s_sub_i32 s37, s5, s34
	s_cmp_ge_u32 s5, s34
	s_cselect_b32 s36, s54, s36
	s_cselect_b32 s5, s37, s5
	s_add_i32 s37, s36, 1
	s_cmp_ge_u32 s5, s34
	s_cselect_b32 s5, s37, s36
	s_xor_b32 s5, s5, s35
	s_sub_i32 s54, s5, s35
	s_mul_i32 s5, s54, s23
	s_sub_i32 s4, s4, s5
	s_add_i32 s55, s22, s4
